# row-statistic slot loads of the RMS epilogues issued together (4 per lane) instead of one round trip each
# speedup vs baseline: 1.0028x; 1.0028x over previous
;     __device__ __forceinline__ void stats(const f32x4 (&v)[2][2][4][2], const Unit& u, int wr, int wc, int fr, int fq, LAS unsigned char* lds, int wid, int lane, const RmsX& e) const {
;     ...
;         asm volatile("s_waitcnt vmcnt(0) lgkmcnt(0)" ::: "memory"); __builtin_amdgcn_s_barrier(); asm volatile("" ::: "memory");
;         if (lane < 32) { const unsigned* sl = (const unsigned*)(e.slots + (size_t)(u.pm * BM + row) * 4); float t = 0.f;
; #pragma unroll
;             for (int k = 0; k < 4; ++k) t += __uint_as_float(__hip_atomic_load(sl + k, __ATOMIC_RELAXED, __HIP_MEMORY_SCOPE_AGENT));
;             S[row] = rsqrtf(t * (1.f / 1024.f) + EPS); }
.LBB0_254:
	s_waitcnt vmcnt(0) lgkmcnt(0)
	s_barrier
	s_lshl_b32 s0, s18, 8
	v_add_u32_e32 v0, s0, v174
	s_waitcnt lgkmcnt(0)
	v_ashrrev_i32_e32 v1, 31, v0
	s_and_saveexec_b64 s[30:31], s[6:7]
	s_cbranch_execz .LBB0_256
	v_lshl_add_u64 v[132:133], v[0:1], 4, s[14:15]
	global_load_dword v134, v[132:133], off sc1
	global_load_dword v135, v[132:133], off offset:4 sc1
	global_load_dword v140, v[132:133], off offset:8 sc1
	s_nop 0
	global_load_dword v132, v[132:133], off offset:12 sc1
	s_waitcnt vmcnt(3)
	v_add_f32_e32 v134, 0, v134
	s_waitcnt vmcnt(2)
	v_add_f32_e32 v134, v134, v135
	s_waitcnt vmcnt(1)
	v_add_f32_e32 v134, v134, v140
	s_waitcnt vmcnt(0)
	v_add_f32_e32 v132, v134, v132
	v_fmamk_f32 v132, v132, 0x3a800000, v204
	v_cmp_gt_f32_e32 vcc, s93, v132
	v_mul_f32_e32 v133, 0x4b800000, v132
	s_nop 0
	v_cndmask_b32_e32 v132, v132, v133, vcc
	v_rsq_f32_e32 v132, v132
	s_nop 0
	v_mul_f32_e32 v133, 0x45800000, v132
	v_cndmask_b32_e32 v132, v132, v133, vcc
	v_lshl_add_u32 v133, v174, 2, 0
	ds_write_b32 v133, v132 offset:4096

;     __device__ __forceinline__ void stats(const f32x4 (&v)[2][2][4][2], const Unit& u, int wr, int wc, int fr, int fq, LAS unsigned char* lds, int wid, int lane, const RmsX& e) const {
;     ...
;         asm volatile("s_waitcnt vmcnt(0) lgkmcnt(0)" ::: "memory"); __builtin_amdgcn_s_barrier(); asm volatile("" ::: "memory");
;         if (lane < 32) { const unsigned* sl = (const unsigned*)(e.slots + (size_t)(u.pm * BM + row) * 4); float t = 0.f;
; #pragma unroll
;             for (int k = 0; k < 4; ++k) t += __uint_as_float(__hip_atomic_load(sl + k, __ATOMIC_RELAXED, __HIP_MEMORY_SCOPE_AGENT));
;             S[row] = rsqrtf(t * (1.f / 1024.f) + EPS); }
.LBB0_488:
	s_waitcnt vmcnt(0) lgkmcnt(0)
	s_barrier
	s_lshl_b32 s41, s35, 8
	v_add_u32_e32 v146, s41, v161
	v_ashrrev_i32_e32 v147, 31, v146
	s_and_saveexec_b64 s[10:11], s[6:7]
	s_cbranch_execz .LBB0_490
	s_waitcnt lgkmcnt(0)
	v_lshl_add_u64 v[0:1], v[146:147], 4, s[12:13]
	global_load_dword v132, v[0:1], off sc1
	global_load_dword v133, v[0:1], off offset:4 sc1
	global_load_dword v134, v[0:1], off offset:8 sc1
	s_nop 0
	global_load_dword v0, v[0:1], off offset:12 sc1
	s_waitcnt vmcnt(3)
	v_add_f32_e32 v132, 0, v132
	s_waitcnt vmcnt(2)
	v_add_f32_e32 v132, v132, v133
	s_waitcnt vmcnt(1)
	v_add_f32_e32 v132, v132, v134
	s_waitcnt vmcnt(0)
	v_add_f32_e32 v0, v132, v0
	v_fmamk_f32 v0, v0, 0x3a800000, v204
	v_cmp_gt_f32_e32 vcc, s93, v0
	v_mul_f32_e32 v1, 0x4b800000, v0
	s_nop 0
	v_cndmask_b32_e32 v0, v0, v1, vcc
	v_rsq_f32_e32 v0, v0
	s_nop 0
	v_mul_f32_e32 v1, 0x45800000, v0
	v_cndmask_b32_e32 v0, v0, v1, vcc
	v_lshl_add_u32 v1, v161, 2, 0
	ds_write_b32 v1, v0 offset:4096
